# s5_scan piece loop: next piece's 4 E-tile loads issued right after the current ds_writes and waited once before the stores (was 4 serialized load->vmcnt(0)->ds_write round trips per piece)
# speedup vs baseline: 1.0062x; 1.0062x over previous
; #define LAS __attribute__((address_space(3)))
; __device__ __forceinline__ int lane_id() { int l; asm volatile("v_mbcnt_lo_u32_b32 %0, -1, 0\n\tv_mbcnt_hi_u32_b32 %0, -1, %0" : "=v"(l)); return l; }
; __device__ __forceinline__ void lam_pow(float ar, float ai, float dt, float d, float& pr, float& pi) { const float m = __expf(d * ar * dt); float s, c; sincosf(d * ai * dt, &s, &c); pr = m * c; pi = m * s; }
; #define lane lane_id()
; __device__ __forceinline__ void s5_scan(const Prm& P, LAS unsigned char* lds, int item, int wave) {
;     const int lane = lane_id(), tid = wave * 64 + lane, nl = tid & 31, ss = tid >> 5, b = item >> 6, g = (item >> 1) & 31, half = item & 1, n = half * 32 + nl;
;     const float dt = __expf(P.in[I_LOGDT][g]); const float ar = P.in[I_ARE][g * 64 + n], ai = P.in[I_AIM][g * 64 + n];
;     float Lr, Li; lam_pow(ar, ai, dt, 16.0f, Lr, Li);
;     float L8r = Lr, L8i = Li;
; #pragma unroll
;     for (int q = 0; q < 3; ++q) { const float a = L8r * L8r - L8i * L8i, c = 2.0f * L8r * L8i; L8r = a; L8i = c; }
;     LAS float* tile = (LAS float*)lds; LAS float* agg = tile + 128 * 64;
;     const float* E = (const float*)(P.ws + WS_E); bf16_t* A5 = (bf16_t*)(P.ws + WS_A5);
;     float car = 0.f, cai = 0.f;
;     for (int piece = 0; piece < 4; ++piece) {
;         const size_t rowbase = (size_t)g * 2048 + b * 512 + piece * 128;
; #pragma unroll
;         for (int i = 0; i < 4; ++i) { const int idx = tid + i * 512, r = idx >> 4, part = (idx >> 3) & 1, c4 = idx & 7;
;             *(LAS f32x4*)(tile + r * 64 + part * 32 + c4 * 4) = *(const f32x4*)(E + (rowbase + r) * 128 + part * 64 + half * 32 + c4 * 4); }
.LBB0_815:
	s_andn2_saveexec_b64 s[4:5], s[10:11]
	v_mul_f32_e64 v0, |v2|, s50
	v_rndne_f32_e32 v9, v0
	v_cvt_i32_f32_e32 v8, v9
	v_fma_f32 v0, v9, s51, |v2|
	v_fmac_f32_e32 v0, 0xb3a22168, v9
	v_fmac_f32_e32 v0, 0xa7c234c4, v9
	s_or_b64 exec, exec, s[4:5]
	s_waitcnt vmcnt(0)
	v_mul_f32_e32 v5, 0x41800000, v5
	v_mul_f32_e32 v5, v7, v5
	v_mul_f32_e32 v7, v0, v0
	v_fmamk_f32 v9, v7, 0xb94c1982, v24
	v_fmaak_f32 v9, v7, v9, 0xbe2aaa9d
	v_mul_f32_e32 v9, v7, v9
	v_fmac_f32_e32 v0, v0, v9
	v_fmamk_f32 v9, v7, 0x37d75334, v25
	v_fmaak_f32 v9, v7, v9, 0x3d2aabf7
	v_fmaak_f32 v9, v7, v9, 0xbf000004
	v_fma_f32 v7, v7, v9, 1.0
	v_lshlrev_b32_e32 v9, 30, v8
	v_and_b32_e32 v8, 1, v8
	v_mul_f32_e32 v5, 0x3fb8aa3b, v5
	v_cmp_eq_u32_e32 vcc, 0, v8
	s_lshr_b32 s4, s60, 1
	v_exp_f32_e32 v5, v5
	v_cndmask_b32_e32 v8, v7, v0, vcc
	v_xor_b32_e32 v4, v4, v2
	v_xor_b32_e32 v0, 0x80000000, v0
	s_and_b32 s4, s4, 31
	v_and_b32_e32 v10, 0x80000000, v9
	v_xor_b32_e32 v4, v4, v8
	v_cndmask_b32_e32 v0, v0, v7, vcc
	s_lshl_b32 s36, s4, 11
	v_readlane_b32 s4, v255, 9
	v_xor_b32_e32 v4, v4, v10
	v_bitop3_b32 v0, v0, v9, s52 bitop3:0x78
	v_cmp_class_f32_e64 vcc, v2, s53
	v_add_u32_e32 v21, s4, v6
	v_bfe_u32 v50, v6, 3, 1
	v_cndmask_b32_e32 v0, v28, v0, vcc
	v_cndmask_b32_e32 v2, v28, v4, vcc
	v_lshlrev_b32_e32 v6, 4, v6
	v_mul_f32_e32 v0, v5, v0
	v_mul_f32_e32 v29, v5, v2
	v_and_b32_e32 v51, 0x70, v6
	v_add_u32_e32 v6, 0x200, v21
	v_ashrrev_i32_e32 v16, 4, v6
	v_add_u32_e32 v6, 0x400, v21
	v_fmamk_f32 v32, v29, 0x80000000, v0
	v_ashrrev_i32_e32 v18, 4, v6
	v_add_u32_e32 v6, 0x600, v21
	v_fma_f32 v33, 0, v0, v29
	v_mul_f32_e32 v35, v29, v32
	v_ashrrev_i32_e32 v48, 4, v6
	v_mul_f32_e32 v6, v29, v33
	v_fmac_f32_e32 v35, v0, v33
	v_add_f32_e32 v4, v0, v0
	v_fma_f32 v34, v0, v32, -v6
	v_mul_f32_e32 v37, v0, v35
	v_mul_f32_e32 v2, v29, v29
	v_mul_f32_e32 v5, v29, v4
	v_mul_f32_e32 v6, v29, v35
	v_fmac_f32_e32 v37, v29, v34
	v_fma_f32 v2, v0, v0, -v2
	v_mul_f32_e32 v4, v5, v5
	v_fma_f32 v36, v0, v34, -v6
	v_mul_f32_e32 v39, v0, v37
	v_fma_f32 v4, v2, v2, -v4
	v_mul_f32_e32 v6, v29, v37
	v_fmac_f32_e32 v39, v29, v36
	v_add_f32_e32 v9, v2, v2
	v_mov_b32_e32 v8, v4
	v_fma_f32 v38, v0, v36, -v6
	v_mul_f32_e32 v41, v0, v39
	s_and_b32 s37, s3, 0xfffffe00
	s_bfe_u32 s63, s2, 0x10005
	v_pk_mul_f32 v[8:9], v[4:5], v[8:9]
	v_mul_f32_e32 v6, v29, v39
	v_fmac_f32_e32 v41, v29, v38
	s_ashr_i32 s62, s37, 31
	s_lshl_b32 s64, s63, 7
	v_pk_mov_b32 v[4:5], v[8:9], v[4:5] op_sel:[1,0]
	v_mov_b32_e32 v2, v9
	v_fma_f32 v40, v0, v38, -v6
	v_mul_f32_e32 v43, v0, v41
	v_ashrrev_i32_e32 v23, 5, v21
	v_pk_mul_f32 v[10:11], v[4:5], v[2:3]
	v_ashrrev_i32_e32 v14, 4, v21
	v_mul_f32_e32 v6, v29, v41
	v_fmac_f32_e32 v43, v29, v40
	s_add_u32 s36, s36, s37
	v_pk_fma_f32 v[12:13], v[4:5], v[2:3], v[8:9] neg_lo:[1,0,0] neg_hi:[1,0,0]
	v_pk_mul_f32 v[10:11], v[8:9], v[10:11]
	v_lshlrev_b32_e32 v46, 3, v23
	v_ashrrev_i32_e32 v15, 31, v14
	v_ashrrev_i32_e32 v17, 31, v16
	v_ashrrev_i32_e32 v19, 31, v18
	v_ashrrev_i32_e32 v49, 31, v48
	v_fma_f32 v42, v0, v40, -v6
	v_mul_f32_e32 v6, v29, v43
	s_addc_u32 s37, 0, s62
	v_mov_b32_e32 v4, v12
	v_mov_b32_e32 v5, v11
	v_ashrrev_i32_e32 v47, 31, v46
	v_lshlrev_b32_e32 v54, 8, v14
	v_lshlrev_b32_e32 v55, 8, v16
	v_lshlrev_b32_e32 v56, 8, v18
	v_fma_f32 v44, v0, v42, -v6
	v_mov_b32_e32 v6, v12
	v_mov_b32_e32 v7, v12
	v_mov_b32_e32 v8, v11
	v_mov_b32_e32 v9, v11
	v_pk_mov_b32 v[10:11], v[10:11], v[12:13] op_sel:[1,0]
	v_lshl_add_u64 v[12:13], s[36:37], 0, v[14:15]
	v_lshl_add_u64 v[14:15], s[36:37], 0, v[16:17]
	v_lshl_add_u64 v[16:17], s[36:37], 0, v[18:19]
	v_lshl_add_u64 v[18:19], s[36:37], 0, v[48:49]
	v_lshlrev_b32_e32 v2, 7, v50
	v_cmp_gt_u32_e64 s[4:5], 32, v21
	v_lshlrev_b64 v[12:13], 9, v[12:13]
	v_lshlrev_b32_e32 v21, 8, v50
	v_lshlrev_b64 v[14:15], 9, v[14:15]
	v_lshlrev_b64 v[16:17], 9, v[16:17]
	v_lshlrev_b64 v[18:19], 9, v[18:19]
	v_lshl_add_u64 v[46:47], s[36:37], 0, v[46:47]
	v_add3_u32 v52, 0, v2, v51
	v_lshl_add_u32 v2, v20, 2, 0
	v_lshlrev_b32_e32 v57, 8, v48
	v_or_b32_e32 v12, v12, v21
	v_or_b32_e32 v14, v14, v21
	v_or_b32_e32 v16, v16, v21
	v_or_b32_e32 v18, v18, v21
	v_mad_u64_u32 v[48:49], s[36:37], v46, s54, 0
	v_lshl_add_u32 v53, v23, 8, v2
	v_lshlrev_b32_e32 v58, 11, v23
	v_mov_b32_e32 v22, 0
	v_mul_f32_e32 v30, 0, v29
	v_mul_f32_e32 v45, v0, v43
	v_or3_b32 v12, v12, s64, v51
	v_or3_b32 v14, v14, s64, v51
	v_or3_b32 v16, v16, s64, v51
	v_or3_b32 v18, v18, s64, v51
	v_lshlrev_b32_e32 v20, 1, v20
	s_lshl_b32 s36, s63, 6
	s_mov_b32 s61, 4
	v_cmp_eq_u32_e32 vcc, 15, v23
	v_fma_f32 v31, v0, 0, -v30
	v_fmac_f32_e32 v30, 0, v0
	v_cmp_eq_u32_e64 s[6:7], 1, v23
	v_cmp_eq_u32_e64 s[8:9], 2, v23
	v_cmp_eq_u32_e64 s[10:11], 3, v23
	v_cmp_eq_u32_e64 s[12:13], 4, v23
	v_cmp_eq_u32_e64 s[14:15], 5, v23
	v_cmp_eq_u32_e64 s[16:17], 6, v23
	v_cmp_eq_u32_e64 s[18:19], 7, v23
	v_cmp_eq_u32_e64 s[20:21], 8, v23
	v_cmp_eq_u32_e64 s[22:23], 9, v23
	v_cmp_eq_u32_e64 s[24:25], 10, v23
	v_cmp_eq_u32_e64 s[26:27], 11, v23
	v_cmp_eq_u32_e64 s[28:29], 12, v23
	v_cmp_eq_u32_e64 s[30:31], 13, v23
	v_cmp_eq_u32_e64 s[34:35], 14, v23
	v_fmac_f32_e32 v45, v29, v42
	v_lshl_add_u64 v[12:13], v[12:13], 0, s[38:39]
	v_lshl_add_u64 v[14:15], v[14:15], 0, s[38:39]
	v_lshl_add_u64 v[16:17], v[16:17], 0, s[38:39]
	v_lshl_add_u64 v[18:19], v[18:19], 0, s[38:39]
	v_mad_i32_i24 v21, v47, s54, v49
	v_or3_b32 v20, s36, v20, v48
	v_add_u32_e32 v46, v52, v54
	v_add_u32_e32 v47, v52, v55
	v_add_u32_e32 v48, v52, v56
	v_add_u32_e32 v49, v52, v57
	v_add_u32_e32 v50, v2, v58
	v_add_u32_e32 v51, 0x8000, v53
	v_mov_b32_e32 v23, v22
	v_lshl_add_u64 v[52:53], s[92:93], 0, v[12:13]
	global_load_dwordx4 v[224:227], v[52:53], off
	v_lshl_add_u64 v[52:53], s[92:93], 0, v[14:15]
	global_load_dwordx4 v[228:231], v[52:53], off
	v_lshl_add_u64 v[52:53], s[92:93], 0, v[16:17]
	global_load_dwordx4 v[232:235], v[52:53], off
	v_lshl_add_u64 v[52:53], s[92:93], 0, v[18:19]
	global_load_dwordx4 v[236:239], v[52:53], off
	v_lshl_add_u64 v[12:13], v[12:13], 0, s[44:45]
	v_lshl_add_u64 v[14:15], v[14:15], 0, s[44:45]
	v_lshl_add_u64 v[16:17], v[16:17], 0, s[44:45]
	v_lshl_add_u64 v[18:19], v[18:19], 0, s[44:45]
	s_waitcnt vmcnt(0)
; #define LAS __attribute__((address_space(3)))
; __device__ __forceinline__ void s5_scan(const Prm& P, LAS unsigned char* lds, int item, int wave) {
;     ...
;         for (int i = 0; i < 4; ++i) { const int idx = tid + i * 512, r = idx >> 4, part = (idx >> 3) & 1, c4 = idx & 7;
;             *(LAS f32x4*)(tile + r * 64 + part * 32 + c4 * 4) = *(const f32x4*)(E + (rowbase + r) * 128 + part * 64 + half * 32 + c4 * 4); }
;         __syncthreads();
;         const int r0 = ss * 8; float xr[8], xi[8]; float pr = 0.f, pi = 0.f;
; #pragma unroll
;         for (int j = 0; j < 8; ++j) { xr[j] = pr; xi[j] = pi; const float er = tile[(r0 + j) * 64 + nl], ei = tile[(r0 + j) * 64 + 32 + nl];
;             const float a = Lr * pr - Li * pi + er, c = Lr * pi + Li * pr + ei; pr = a; pi = c; }
;         agg[ss * 64 + nl] = pr; agg[ss * 64 + 32 + nl] = pi;
;         __syncthreads();
;         float cr = car, ci = cai, mr = 0.f, mi = 0.f;
; #pragma unroll
;         for (int s2 = 0; s2 < 16; ++s2) { if (s2 == ss) { mr = cr; mi = ci; } const float a = L8r * cr - L8i * ci + agg[s2 * 64 + nl], c = L8r * ci + L8i * cr + agg[s2 * 64 + 32 + nl]; cr = a; ci = c; }
.LBB0_818:
	v_add_u32_e32 v68, 0x400, v50
	v_add_u32_e32 v72, 0x8000, v2
	v_cndmask_b32_e64 v69, 0, v23, s[4:5]
	v_add_u32_e32 v76, 0x8400, v2
	v_add_u32_e32 v80, 0x8c00, v2
	s_add_i32 s61, s61, -1
	s_cmp_lg_u32 s61, 0
	ds_write_b128 v46, v[224:227]
	ds_write_b128 v47, v[228:231]
	ds_write_b128 v48, v[232:235]
	ds_write_b128 v49, v[236:239]
	v_lshl_add_u64 v[52:53], s[92:93], 0, v[12:13]
	global_load_dwordx4 v[224:227], v[52:53], off
	v_lshl_add_u64 v[52:53], s[92:93], 0, v[14:15]
	global_load_dwordx4 v[228:231], v[52:53], off
	v_lshl_add_u64 v[52:53], s[92:93], 0, v[16:17]
	global_load_dwordx4 v[232:235], v[52:53], off
	v_lshl_add_u64 v[52:53], s[92:93], 0, v[18:19]
	global_load_dwordx4 v[236:239], v[52:53], off
	v_lshl_add_u64 v[12:13], v[12:13], 0, s[44:45]
	v_lshl_add_u64 v[14:15], v[14:15], 0, s[44:45]
	v_lshl_add_u64 v[16:17], v[16:17], 0, s[44:45]
	v_lshl_add_u64 v[18:19], v[18:19], 0, s[44:45]
	s_waitcnt lgkmcnt(0)
	s_barrier
	ds_read2_b32 v[52:53], v50 offset1:32
	ds_read2_b32 v[60:61], v50 offset0:192 offset1:224
	ds_read2_b32 v[66:67], v68 offset0:128 offset1:160
	s_waitcnt lgkmcnt(2)
	v_add_f32_e32 v59, v31, v52
	v_add_f32_e32 v57, v30, v53
	ds_read2_b32 v[52:53], v50 offset0:64 offset1:96
	v_mul_f32_e32 v54, v29, v57
	v_fma_f32 v54, v0, v59, -v54
	s_waitcnt lgkmcnt(0)
	v_add_f32_e32 v58, v52, v54
	v_mul_f32_e32 v52, v0, v57
	v_fmac_f32_e32 v52, v29, v59
	v_add_f32_e32 v55, v53, v52
	ds_read2_b32 v[52:53], v50 offset0:128 offset1:160
	v_mul_f32_e32 v54, v29, v55
	v_fma_f32 v54, v0, v58, -v54
	s_waitcnt lgkmcnt(0)
	v_add_f32_e32 v56, v52, v54
	v_mul_f32_e32 v52, v29, v58
	v_fmac_f32_e32 v52, v0, v55
	v_add_f32_e32 v53, v53, v52
	v_mul_f32_e32 v52, v29, v53
	v_fma_f32 v52, v0, v56, -v52
	v_add_f32_e32 v54, v60, v52
	v_mul_f32_e32 v52, v29, v56
	v_fmac_f32_e32 v52, v0, v53
	v_add_f32_e32 v52, v61, v52
	ds_read2_b32 v[60:61], v68 offset1:32
	v_mul_f32_e32 v62, v29, v52
	v_fma_f32 v62, v0, v54, -v62
	s_waitcnt lgkmcnt(0)
	v_add_f32_e32 v65, v60, v62
	v_mul_f32_e32 v60, v29, v54
	v_fmac_f32_e32 v60, v0, v52
	v_add_f32_e32 v63, v61, v60
	ds_read2_b32 v[60:61], v68 offset0:64 offset1:96
	v_mul_f32_e32 v62, v29, v63
	v_fma_f32 v62, v0, v65, -v62
	s_waitcnt lgkmcnt(0)
	v_add_f32_e32 v64, v60, v62
	v_mul_f32_e32 v60, v29, v65
	v_fmac_f32_e32 v60, v0, v63
	v_add_f32_e32 v61, v61, v60
	v_mul_f32_e32 v60, v29, v61
	v_fma_f32 v60, v0, v64, -v60
	v_add_f32_e32 v62, v66, v60
	v_mul_f32_e32 v60, v29, v64
	v_fmac_f32_e32 v60, v0, v61
	v_add_f32_e32 v60, v67, v60
	ds_read2_b32 v[66:67], v68 offset0:192 offset1:224
	v_mul_f32_e32 v68, v29, v60
	v_fma_f32 v68, v0, v62, -v68
	s_waitcnt lgkmcnt(0)
	v_add_f32_e32 v66, v66, v68
	v_mul_f32_e32 v68, v29, v62
	v_fmac_f32_e32 v68, v0, v60
	v_add_f32_e32 v67, v67, v68
	ds_write2_b32 v51, v66, v67 offset1:32
	v_pk_mul_f32 v[66:67], v[4:5], v[22:23]
	s_waitcnt lgkmcnt(0)
	s_barrier
	v_sub_f32_e32 v70, v66, v67
	ds_read2_b32 v[66:67], v72 offset1:32
	v_cndmask_b32_e64 v68, 0, v22, s[4:5]
	v_pk_mul_f32 v[22:23], v[10:11], v[22:23]
	s_waitcnt lgkmcnt(0)
	v_add_f32_e32 v66, v70, v66
	v_add_f32_e32 v22, v22, v23
	v_add_f32_e32 v22, v22, v67
	v_cndmask_b32_e64 v74, v68, v66, s[6:7]
	v_cndmask_b32_e64 v75, v69, v22, s[6:7]
	ds_read2_b32 v[68:69], v72 offset0:64 offset1:96
	v_pk_mul_f32 v[22:23], v[10:11], v[22:23] op_sel_hi:[1,0]
	s_nop 0
	v_pk_fma_f32 v[70:71], v[4:5], v[66:67], v[22:23] neg_lo:[0,0,1] neg_hi:[0,0,1]
	v_pk_fma_f32 v[22:23], v[4:5], v[66:67], v[22:23] op_sel_hi:[1,0,1]
	s_nop 0
	v_mov_b32_e32 v71, v23
	ds_read2_b32 v[22:23], v72 offset0:128 offset1:160
	ds_read2_b32 v[66:67], v72 offset0:192 offset1:224
	s_waitcnt lgkmcnt(2)
	v_pk_add_f32 v[68:69], v[68:69], v[70:71]
	ds_read2_b32 v[72:73], v76 offset1:32
	v_pk_mul_f32 v[70:71], v[8:9], v[68:69]
	v_cndmask_b32_e64 v77, v74, v68, s[8:9]
	v_cndmask_b32_e64 v78, v75, v69, s[8:9]
	v_pk_fma_f32 v[74:75], v[6:7], v[68:69], v[70:71] op_sel:[0,0,1] op_sel_hi:[1,1,0] neg_lo:[0,0,1] neg_hi:[0,0,1]
	v_pk_fma_f32 v[68:69], v[6:7], v[68:69], v[70:71] op_sel:[0,0,1] op_sel_hi:[1,1,0]
	s_nop 0
	v_mov_b32_e32 v75, v69
	s_waitcnt lgkmcnt(2)
	v_pk_add_f32 v[22:23], v[22:23], v[74:75]
	s_nop 0
	v_pk_mul_f32 v[68:69], v[8:9], v[22:23]
	v_cndmask_b32_e64 v74, v77, v22, s[10:11]
	v_cndmask_b32_e64 v75, v78, v23, s[10:11]
	v_pk_fma_f32 v[70:71], v[6:7], v[22:23], v[68:69] op_sel:[0,0,1] op_sel_hi:[1,1,0] neg_lo:[0,0,1] neg_hi:[0,0,1]
	v_pk_fma_f32 v[22:23], v[6:7], v[22:23], v[68:69] op_sel:[0,0,1] op_sel_hi:[1,1,0]
	s_nop 0
	v_mov_b32_e32 v71, v23
	s_waitcnt lgkmcnt(1)
	v_pk_add_f32 v[22:23], v[66:67], v[70:71]
	s_nop 0
	v_pk_mul_f32 v[66:67], v[8:9], v[22:23]
	v_cndmask_b32_e64 v70, v74, v22, s[12:13]
	v_cndmask_b32_e64 v71, v75, v23, s[12:13]
	v_pk_fma_f32 v[68:69], v[6:7], v[22:23], v[66:67] op_sel:[0,0,1] op_sel_hi:[1,1,0] neg_lo:[0,0,1] neg_hi:[0,0,1]
	v_pk_fma_f32 v[22:23], v[6:7], v[22:23], v[66:67] op_sel:[0,0,1] op_sel_hi:[1,1,0]
	s_nop 0
	v_mov_b32_e32 v69, v23
	s_waitcnt lgkmcnt(0)
	v_pk_add_f32 v[22:23], v[72:73], v[68:69]
	ds_read2_b32 v[68:69], v76 offset0:64 offset1:96
	v_cndmask_b32_e64 v77, v70, v22, s[14:15]
	v_mul_f32_e32 v66, v5, v23
	v_mul_f32_e32 v70, v10, v22
	v_cndmask_b32_e64 v78, v71, v23, s[14:15]
	v_pk_fma_f32 v[66:67], v[4:5], v[22:23], v[66:67] op_sel_hi:[1,1,0] neg_lo:[0,0,1] neg_hi:[0,0,1]
	v_pk_fma_f32 v[22:23], v[10:11], v[22:23], v[70:71] op_sel_hi:[1,1,0]
	ds_read2_b32 v[70:71], v76 offset0:128 offset1:160
	ds_read2_b32 v[72:73], v76 offset0:192 offset1:224
	v_mov_b32_e32 v67, v23
	s_waitcnt lgkmcnt(2)
; __device__ __forceinline__ unsigned f2bf(float f) { unsigned u = __builtin_bit_cast(unsigned, f); return (u + 0x7fffu + ((u >> 16) & 1u)) >> 16; }
; __device__ __forceinline__ void s5_scan(const Prm& P, LAS unsigned char* lds, int item, int wave) {
;     ...
;         for (int s2 = 0; s2 < 16; ++s2) { if (s2 == ss) { mr = cr; mi = ci; } const float a = L8r * cr - L8i * ci + agg[s2 * 64 + nl], c = L8r * ci + L8i * cr + agg[s2 * 64 + 32 + nl]; cr = a; ci = c; }
;         car = cr; cai = ci;
;         float pwr = 1.f, pwi = 0.f;
; #pragma unroll
;         for (int j = 0; j < 8; ++j) { const float hr = xr[j] + pwr * mr - pwi * mi, hi = xi[j] + pwr * mi + pwi * mr;
;             bf16_t* dst = A5 + (rowbase + r0 + j) * 384 + 256 + n; dst[0] = (bf16_t)f2bf(hr); dst[64] = (bf16_t)f2bf(hi);
	v_pk_add_f32 v[22:23], v[68:69], v[66:67]
	v_add_u32_e32 v76, 0x8800, v2
	v_pk_mul_f32 v[66:67], v[8:9], v[22:23]
	v_cndmask_b32_e64 v77, v77, v22, s[16:17]
	v_cndmask_b32_e64 v78, v78, v23, s[16:17]
	v_pk_fma_f32 v[68:69], v[6:7], v[22:23], v[66:67] op_sel:[0,0,1] op_sel_hi:[1,1,0] neg_lo:[0,0,1] neg_hi:[0,0,1]
	v_pk_fma_f32 v[22:23], v[6:7], v[22:23], v[66:67] op_sel:[0,0,1] op_sel_hi:[1,1,0]
	ds_read2_b32 v[74:75], v76 offset1:32
	v_mov_b32_e32 v69, v23
	s_waitcnt lgkmcnt(2)
	v_pk_add_f32 v[22:23], v[70:71], v[68:69]
	s_nop 0
	v_pk_mul_f32 v[66:67], v[8:9], v[22:23]
	v_cndmask_b32_e64 v70, v77, v22, s[18:19]
	v_cndmask_b32_e64 v71, v78, v23, s[18:19]
	v_pk_fma_f32 v[68:69], v[6:7], v[22:23], v[66:67] op_sel:[0,0,1] op_sel_hi:[1,1,0] neg_lo:[0,0,1] neg_hi:[0,0,1]
	v_pk_fma_f32 v[22:23], v[6:7], v[22:23], v[66:67] op_sel:[0,0,1] op_sel_hi:[1,1,0]
	s_nop 0
	v_mov_b32_e32 v69, v23
	s_waitcnt lgkmcnt(1)
	v_pk_add_f32 v[22:23], v[72:73], v[68:69]
	s_nop 0
	v_pk_mul_f32 v[66:67], v[8:9], v[22:23]
	v_cndmask_b32_e64 v70, v70, v22, s[20:21]
	v_cndmask_b32_e64 v71, v71, v23, s[20:21]
	v_pk_fma_f32 v[68:69], v[6:7], v[22:23], v[66:67] op_sel:[0,0,1] op_sel_hi:[1,1,0] neg_lo:[0,0,1] neg_hi:[0,0,1]
	v_pk_fma_f32 v[22:23], v[6:7], v[22:23], v[66:67] op_sel:[0,0,1] op_sel_hi:[1,1,0]
	s_nop 0
	v_mov_b32_e32 v69, v23
	s_waitcnt lgkmcnt(0)
	v_pk_add_f32 v[22:23], v[74:75], v[68:69]
	s_nop 0
	v_cndmask_b32_e64 v78, v70, v22, s[22:23]
	v_cndmask_b32_e64 v79, v71, v23, s[22:23]
	ds_read2_b32 v[66:67], v76 offset0:64 offset1:96
	ds_read2_b32 v[68:69], v76 offset0:128 offset1:160
	ds_read2_b32 v[70:71], v76 offset0:192 offset1:224
	v_pk_mul_f32 v[74:75], v[8:9], v[22:23]
	ds_read2_b32 v[72:73], v80 offset1:32
	v_pk_fma_f32 v[76:77], v[6:7], v[22:23], v[74:75] op_sel:[0,0,1] op_sel_hi:[1,1,0] neg_lo:[0,0,1] neg_hi:[0,0,1]
	v_pk_fma_f32 v[22:23], v[6:7], v[22:23], v[74:75] op_sel:[0,0,1] op_sel_hi:[1,1,0]
	s_nop 0
	v_mov_b32_e32 v77, v23
	s_waitcnt lgkmcnt(3)
	v_pk_add_f32 v[22:23], v[66:67], v[76:77]
	s_nop 0
	v_pk_mul_f32 v[66:67], v[8:9], v[22:23]
	v_cndmask_b32_e64 v76, v78, v22, s[24:25]
	v_cndmask_b32_e64 v77, v79, v23, s[24:25]
	v_pk_fma_f32 v[74:75], v[6:7], v[22:23], v[66:67] op_sel:[0,0,1] op_sel_hi:[1,1,0] neg_lo:[0,0,1] neg_hi:[0,0,1]
	v_pk_fma_f32 v[22:23], v[6:7], v[22:23], v[66:67] op_sel:[0,0,1] op_sel_hi:[1,1,0]
	s_nop 0
	v_mov_b32_e32 v75, v23
	s_waitcnt lgkmcnt(2)
	v_pk_add_f32 v[22:23], v[68:69], v[74:75]
	s_nop 0
	v_pk_mul_f32 v[66:67], v[8:9], v[22:23]
	v_cndmask_b32_e64 v74, v76, v22, s[26:27]
	v_cndmask_b32_e64 v75, v77, v23, s[26:27]
	v_pk_fma_f32 v[68:69], v[6:7], v[22:23], v[66:67] op_sel:[0,0,1] op_sel_hi:[1,1,0] neg_lo:[0,0,1] neg_hi:[0,0,1]
	v_pk_fma_f32 v[22:23], v[6:7], v[22:23], v[66:67] op_sel:[0,0,1] op_sel_hi:[1,1,0]
	s_nop 0
	v_mov_b32_e32 v69, v23
	s_waitcnt lgkmcnt(1)
	v_pk_add_f32 v[22:23], v[70:71], v[68:69]
	s_nop 0
	v_pk_mul_f32 v[66:67], v[8:9], v[22:23]
	v_cndmask_b32_e64 v76, v74, v22, s[28:29]
	v_cndmask_b32_e64 v77, v75, v23, s[28:29]
	v_pk_fma_f32 v[68:69], v[6:7], v[22:23], v[66:67] op_sel:[0,0,1] op_sel_hi:[1,1,0] neg_lo:[0,0,1] neg_hi:[0,0,1]
	v_pk_fma_f32 v[22:23], v[6:7], v[22:23], v[66:67] op_sel:[0,0,1] op_sel_hi:[1,1,0]
	v_lshl_add_u64 v[74:75], s[92:93], 0, v[20:21]
	v_mov_b32_e32 v69, v23
	s_waitcnt lgkmcnt(0)
	v_pk_add_f32 v[68:69], v[72:73], v[68:69]
	ds_read2_b32 v[22:23], v80 offset0:64 offset1:96
	ds_read2_b32 v[66:67], v80 offset0:128 offset1:160
	ds_read2_b32 v[70:71], v80 offset0:192 offset1:224
	v_pk_mul_f32 v[72:73], v[8:9], v[68:69]
	v_cndmask_b32_e64 v78, v76, v68, s[30:31]
	v_cndmask_b32_e64 v79, v77, v69, s[30:31]
	v_pk_fma_f32 v[76:77], v[6:7], v[68:69], v[72:73] op_sel:[0,0,1] op_sel_hi:[1,1,0] neg_lo:[0,0,1] neg_hi:[0,0,1]
	v_pk_fma_f32 v[68:69], v[6:7], v[68:69], v[72:73] op_sel:[0,0,1] op_sel_hi:[1,1,0]
	v_lshl_add_u64 v[20:21], v[20:21], 0, s[46:47]
	v_mov_b32_e32 v77, v69
	s_waitcnt lgkmcnt(2)
	v_pk_add_f32 v[22:23], v[22:23], v[76:77]
	s_nop 0
	v_pk_mul_f32 v[68:69], v[8:9], v[22:23]
	v_cndmask_b32_e64 v76, v78, v22, s[34:35]
	v_cndmask_b32_e64 v77, v79, v23, s[34:35]
	v_pk_fma_f32 v[72:73], v[6:7], v[22:23], v[68:69] op_sel:[0,0,1] op_sel_hi:[1,1,0] neg_lo:[0,0,1] neg_hi:[0,0,1]
	v_pk_fma_f32 v[22:23], v[6:7], v[22:23], v[68:69] op_sel:[0,0,1] op_sel_hi:[1,1,0]
	s_nop 0
	v_mov_b32_e32 v73, v23
	s_waitcnt lgkmcnt(1)
	v_pk_add_f32 v[22:23], v[66:67], v[72:73]
	s_nop 0
	v_pk_mul_f32 v[66:67], v[8:9], v[22:23]
	v_cndmask_b32_e32 v72, v76, v22, vcc
	v_cndmask_b32_e32 v73, v77, v23, vcc
	v_pk_fma_f32 v[68:69], v[6:7], v[22:23], v[66:67] op_sel:[0,0,1] op_sel_hi:[1,1,0] neg_lo:[0,0,1] neg_hi:[0,0,1]
	v_pk_fma_f32 v[22:23], v[6:7], v[22:23], v[66:67] op_sel:[0,0,1] op_sel_hi:[1,1,0]
	v_add_f32_e32 v66, 0, v73
	v_add_f32_e32 v22, 0, v72
	v_fmac_f32_e32 v22, 0x80000000, v73
	v_mov_b32_e32 v69, v23
	v_bfe_u32 v23, v22, 16, 1
	v_add3_u32 v67, v22, v23, s55
	v_add_co_u32_e64 v22, s[36:37], s58, v74
	v_fmac_f32_e32 v66, 0, v72
	s_nop 0
	v_addc_co_u32_e64 v23, s[36:37], 0, v75, s[36:37]
	s_waitcnt vmcnt(0)
; __device__ __forceinline__ unsigned f2bf(float f) { unsigned u = __builtin_bit_cast(unsigned, f); return (u + 0x7fffu + ((u >> 16) & 1u)) >> 16; }
; __device__ __forceinline__ void s5_scan(const Prm& P, LAS unsigned char* lds, int item, int wave) {
;     ...
;         float pwr = 1.f, pwi = 0.f;
; #pragma unroll
;         for (int j = 0; j < 8; ++j) { const float hr = xr[j] + pwr * mr - pwi * mi, hi = xi[j] + pwr * mi + pwi * mr;
;             bf16_t* dst = A5 + (rowbase + r0 + j) * 384 + 256 + n; dst[0] = (bf16_t)f2bf(hr); dst[64] = (bf16_t)f2bf(hi);
;             const float a = pwr * Lr - pwi * Li, c = pwr * Li + pwi * Lr; pwr = a; pwi = c; }
;         __syncthreads();
	global_store_short_d16_hi v[22:23], v67, off offset:512
	v_bfe_u32 v67, v66, 16, 1
	v_fmac_f32_e32 v59, v32, v72
	v_add3_u32 v66, v66, v67, s55
	v_fma_f32 v59, -v33, v73, v59
	global_store_short_d16_hi v[22:23], v66, off offset:640
	v_fmac_f32_e32 v57, v32, v73
	v_bfe_u32 v66, v59, 16, 1
	v_fmac_f32_e32 v57, v33, v72
	v_add3_u32 v59, v59, v66, s55
	global_store_short_d16_hi v[22:23], v59, off offset:1280
	v_bfe_u32 v59, v57, 16, 1
	v_add3_u32 v57, v57, v59, s55
	v_fmac_f32_e32 v58, v34, v72
	global_store_short_d16_hi v[22:23], v57, off offset:1408
	v_fma_f32 v57, -v35, v73, v58
	v_fmac_f32_e32 v55, v34, v73
	v_bfe_u32 v58, v57, 16, 1
	v_fmac_f32_e32 v55, v35, v72
	v_add3_u32 v57, v57, v58, s55
	global_store_short_d16_hi v[22:23], v57, off offset:2048
	v_bfe_u32 v57, v55, 16, 1
	v_add3_u32 v55, v55, v57, s55
	v_fmac_f32_e32 v56, v36, v72
	global_store_short_d16_hi v[22:23], v55, off offset:2176
	v_fma_f32 v55, -v37, v73, v56
	v_fmac_f32_e32 v53, v36, v73
	v_bfe_u32 v56, v55, 16, 1
	v_fmac_f32_e32 v53, v37, v72
	v_add3_u32 v55, v55, v56, s55
	global_store_short_d16_hi v[22:23], v55, off offset:2816
	v_bfe_u32 v55, v53, 16, 1
	v_add3_u32 v53, v53, v55, s55
	v_fmac_f32_e32 v54, v38, v72
	global_store_short_d16_hi v[22:23], v53, off offset:2944
	v_fma_f32 v53, -v39, v73, v54
	v_fmac_f32_e32 v52, v38, v73
	v_bfe_u32 v54, v53, 16, 1
	v_fmac_f32_e32 v52, v39, v72
	v_add3_u32 v53, v53, v54, s55
	global_store_short_d16_hi v[22:23], v53, off offset:3584
	v_bfe_u32 v53, v52, 16, 1
	v_add3_u32 v52, v52, v53, s55
	v_fmac_f32_e32 v65, v40, v72
	global_store_short_d16_hi v[22:23], v52, off offset:3712
	v_fma_f32 v22, -v41, v73, v65
	v_bfe_u32 v23, v22, 16, 1
	v_fmac_f32_e32 v63, v40, v73
	v_add3_u32 v52, v22, v23, s55
	v_add_co_u32_e64 v22, s[36:37], s59, v74
	v_fmac_f32_e32 v63, v41, v72
	s_nop 0
	v_addc_co_u32_e64 v23, s[36:37], 0, v75, s[36:37]
	global_store_short_d16_hi v[22:23], v52, off offset:256
	v_bfe_u32 v52, v63, 16, 1
	v_add3_u32 v52, v63, v52, s55
	v_fmac_f32_e32 v64, v42, v72
	global_store_short_d16_hi v[22:23], v52, off offset:384
	v_fma_f32 v52, -v43, v73, v64
	v_fmac_f32_e32 v61, v42, v73
	v_bfe_u32 v53, v52, 16, 1
	v_fmac_f32_e32 v61, v43, v72
	v_add3_u32 v52, v52, v53, s55
	global_store_short_d16_hi v[22:23], v52, off offset:1024
	v_bfe_u32 v52, v61, 16, 1
	v_add3_u32 v52, v61, v52, s55
	v_fmac_f32_e32 v62, v44, v72
	global_store_short_d16_hi v[22:23], v52, off offset:1152
	v_fma_f32 v52, -v45, v73, v62
	v_fmac_f32_e32 v60, v44, v73
	v_bfe_u32 v53, v52, 16, 1
	v_fmac_f32_e32 v60, v45, v72
	v_add3_u32 v52, v52, v53, s55
	global_store_short_d16_hi v[22:23], v52, off offset:1792
	v_bfe_u32 v52, v60, 16, 1
	v_add3_u32 v52, v60, v52, s55
	global_store_short_d16_hi v[22:23], v52, off offset:1920
	s_waitcnt lgkmcnt(0)
	v_pk_add_f32 v[22:23], v[70:71], v[68:69]
	s_barrier
	s_cbranch_scc1 .LBB0_818
	v_readlane_b32 s4, v255, 1
	s_add_i32 s60, s60, s4
	s_add_i32 s3, s3, s94
	s_add_i32 s2, s2, s33
	s_cmpk_gt_i32 s60, 0xff
	v_readlane_b32 s5, v255, 2
	s_cbranch_scc0 .LBB0_813
	v_writelane_b32 v255, s76, 20
	s_lshl_b32 s2, s97, 1
	s_add_u32 s62, s92, 0xf400000
	v_writelane_b32 v255, s77, 21
	v_writelane_b32 v255, s94, 22
	s_addc_u32 s63, s93, 0
	s_mov_b32 s75, 0
	v_writelane_b32 v255, s95, 23
	v_writelane_b32 v255, s90, 24
	s_mov_b32 s81, s75
	v_mbcnt_lo_u32_b32 v0, -1, 0
	v_writelane_b32 v255, s91, 25
	v_writelane_b32 v255, s2, 26
	s_lshr_b32 s2, s80, 7
	s_add_u32 s64, s92, 0x7400000
	s_addc_u32 s65, s93, 0
	s_add_u32 s66, s92, 0x13400000
	s_addc_u32 s67, s93, 0
	s_add_u32 s4, s92, 0x1c400000
	s_addc_u32 s5, s93, 0
	v_writelane_b32 v255, s4, 27
	s_lshl_b32 s3, s2, 5
	s_lshl_b32 s2, s2, 6
	v_writelane_b32 v255, s5, 28
	s_add_i32 s2, s2, 0
	v_writelane_b32 v255, s3, 29
	s_add_i32 s2, s2, 0x15c00
	v_writelane_b32 v255, s2, 30
	s_and_b32 s2, s80, 64
	v_writelane_b32 v255, s2, 31
	s_lshl_b32 s2, s97, 9
	s_add_i32 s60, s2, 0
	s_lshl_b32 s2, s97, 4
	s_add_i32 s61, s2, 0
	s_lshl_b32 s55, s97, 3
	s_add_i32 s60, s60, 0x20800
	s_add_i32 s58, s61, 0x11400
	s_cmpk_lt_u32 s80, 0xc0
	s_cselect_b64 s[76:77], -1, 0
	s_bfe_u32 s2, s80, 0x20006
	s_cmpk_gt_u32 s80, 0xff
	s_cselect_b64 s[4:5], -1, 0
	s_and_b32 s18, s80, 0xffffff80
	s_lshl_b32 s3, s2, 5
	s_lshl_b32 s2, s2, 7
	s_add_i32 s96, s18, 0
	s_and_b32 s59, s55, 0x1fffffe0
	v_writelane_b32 v255, s3, 32
	s_add_i32 s2, s2, 0
	s_add_i32 s96, s96, 0x21800
	v_writelane_b32 v255, s2, 33
	s_and_b64 s[2:3], s[88:89], exec
	s_mov_b32 s2, s97
	s_cselect_b32 s97, 0, 32
	s_cmp_eq_u32 s2, 2
	s_cselect_b32 s3, 32, 0
	s_cmpk_gt_u32 s80, 0x7f
	s_cselect_b64 s[6:7], -1, 0
	s_cmpk_gt_u32 s80, 0xbf
	s_cselect_b64 s[8:9], -1, 0
	s_cmpk_gt_u32 s80, 0x13f
	s_cselect_b64 s[10:11], -1, 0
	s_cmpk_gt_u32 s80, 0x17f
	s_cselect_b64 s[12:13], -1, 0
	s_cmpk_gt_u32 s80, 0x1bf
	v_writelane_b32 v255, s3, 34
	s_cselect_b64 s[14:15], -1, 0
	s_cmpk_gt_u32 s80, 0x1ff
	s_cselect_b64 s[16:17], -1, 0
	v_writelane_b32 v255, s2, 35
	s_or_b32 s3, s97, 1
	v_writelane_b32 v255, s3, 36
	s_or_b32 s3, s97, 2
	v_writelane_b32 v255, s3, 37
	s_or_b32 s3, s97, 3
	v_writelane_b32 v255, s3, 38
	s_or_b32 s3, s97, 8
	v_writelane_b32 v255, s3, 39
	s_or_b32 s3, s97, 9
	v_writelane_b32 v255, s3, 40
	s_or_b32 s3, s97, 10
	v_writelane_b32 v255, s3, 41
	s_or_b32 s3, s97, 11
	v_writelane_b32 v255, s3, 42
	s_or_b32 s3, s97, 16
	v_writelane_b32 v255, s3, 43
	s_or_b32 s3, s97, 17
	v_writelane_b32 v255, s3, 44
	s_or_b32 s3, s97, 18
	v_writelane_b32 v255, s3, 45
	s_or_b32 s3, s97, 19
	v_writelane_b32 v255, s3, 46
	s_or_b32 s3, s97, 24
	v_writelane_b32 v255, s3, 47
	s_or_b32 s3, s97, 25
	v_writelane_b32 v255, s3, 48
	s_or_b32 s3, s97, 26
	s_mulk_i32 s2, 0x880
	v_writelane_b32 v255, s3, 49
	s_or_b32 s3, s97, 27
	v_writelane_b32 v255, s3, 50
	s_add_i32 s2, s2, 0
	v_writelane_b32 v255, s2, 51
	s_add_u32 s2, s92, s18
	s_addc_u32 s3, s93, 0
	s_add_u32 s2, s2, 0x1f500040
	v_writelane_b32 v255, s2, 52
	s_addc_u32 s2, s3, 0
	v_writelane_b32 v255, s2, 53
	v_mov_b32_e32 v75, 0
	v_readlane_b32 s2, v255, 7
	v_readlane_b32 s3, v255, 8
	s_mov_b32 s20, s2
	s_lshl_b32 s54, s2, 4
	v_readlane_b32 s2, v255, 1
	s_lshl_b32 s2, s2, 4
	v_readlane_b32 s3, v255, 2
	v_writelane_b32 v255, s2, 54
	s_add_u32 s2, s55, 64
	v_writelane_b32 v255, s2, 55
	s_mov_b32 s2, s80
	v_writelane_b32 v255, s2, 56
	s_addc_u32 s90, 0, 0
	v_mbcnt_hi_u32_b32 v108, -1, v0
	v_writelane_b32 v255, s3, 57
	s_lshl_b64 s[2:3], s[80:81], 8
	s_and_b32 s2, s2, 0xffffc000
	s_add_u32 s18, s70, s2
	s_addc_u32 s19, s71, s3
	s_add_u32 s78, s18, 0x20000
	s_addc_u32 s79, s19, 0
	s_add_u32 s80, s92, s2
	s_addc_u32 s81, s93, s3
	s_movk_i32 s3, 0x110
	v_mov_b32_e32 v109, 0x358637bd
	s_movk_i32 s72, 0x90
	s_add_i32 s73, 0, 0x1e400
	s_movk_i32 s95, 0x7fff
	s_mov_b32 s2, s20
	s_mov_b32 s91, s20
	s_movk_i32 s94, 0x210
	s_branch .LBB0_822
